# dilated attention groups 1,2: previous lse / previous output loads issued at the start of the unit so their latency overlaps QK/PV
# speedup vs baseline: 1.0099x; 1.0099x over previous
.LBB0_750:
	s_abs_i32 s1, s4
	s_mul_hi_u32 s2, s1, s72
	s_mul_i32 s3, s2, s41
	s_sub_i32 s1, s1, s3
	s_ashr_i32 s0, s4, 31
	s_add_i32 s3, s2, 1
	s_sub_i32 s4, s1, s41
	s_cmp_ge_u32 s1, s41
	s_cselect_b32 s2, s3, s2
	s_cselect_b32 s1, s4, s1
	s_add_i32 s3, s2, 1
	s_cmp_ge_u32 s1, s41
	s_cselect_b32 s1, s3, s2
	s_xor_b32 s1, s1, s0
	s_sub_i32 s78, s1, s0
	s_andn2_b64 vcc, exec, s[24:25]
	s_cbranch_vccnz .Ldil_nohoist
	s_mul_i32 s0, s74, s78
	s_add_i32 s0, s0, s75
	v_add_u32_e32 v218, s0, v191
	s_ashr_i32 s0, s78, 31
	s_lshr_b32 s0, s0, 28
	s_add_i32 s1, s78, s0
	s_ashr_i32 s2, s1, 4
	s_abs_i32 s3, s2
	s_mul_hi_u32 s4, s3, s73
	s_mul_i32 s5, s4, s40
	s_sub_i32 s3, s3, s5
	s_ashr_i32 s0, s1, 31
	s_add_i32 s5, s4, 1
	s_sub_i32 s6, s3, s40
	s_cmp_ge_u32 s3, s40
	s_cselect_b32 s4, s5, s4
	s_cselect_b32 s3, s6, s3
	s_add_i32 s5, s4, 1
	s_cmp_ge_u32 s3, s40
	s_cselect_b32 s3, s5, s4
	s_xor_b32 s3, s3, s0
	s_sub_i32 s0, s3, s0
	s_mul_i32 s3, s0, s40
	s_and_b32 s1, s1, -16
	s_sub_i32 s3, s2, s3
	s_sub_i32 s2, s78, s1
	s_ashr_i32 s1, s0, 31
	s_lshl_b64 s[0:1], s[0:1], 13
	s_ashr_i32 s4, s3, 31
	s_add_u32 s0, s0, s3
	s_addc_u32 s1, s1, s4
	v_ashrrev_i32_e32 v219, 31, v218
	s_ashr_i32 s3, s2, 31
	v_lshlrev_b64 v[218:219], s71, v[218:219]
	s_lshl_b32 s4, s2, 6
	v_lshl_add_u64 v[218:219], s[0:1], 0, v[218:219]
	s_ashr_i32 s5, s4, 31
	v_lshlrev_b64 v[220:221], 6, v[218:219]
	v_lshlrev_b32_e32 v222, 1, v144
	v_lshl_add_u64 v[220:221], s[28:29], 0, v[220:221]
	v_lshlrev_b64 v[218:219], 11, v[218:219]
	v_lshl_add_u64 v[220:221], s[2:3], 2, v[220:221]
	v_lshl_add_u64 v[218:219], s[26:27], 0, v[218:219]
	global_load_dword v217, v[220:221], off
	v_lshl_add_u64 v[218:219], s[4:5], 1, v[218:219]
	s_nop 0
	v_mad_u64_u32 v[220:221], s[6:7], v222, 1, v[218:219]
	s_nop 0
	global_load_dwordx2 v[236:237], v[220:221], off
	global_load_dwordx2 v[238:239], v[220:221], off offset:16
	global_load_dwordx2 v[240:241], v[220:221], off offset:32
	global_load_dwordx2 v[242:243], v[220:221], off offset:48
	global_load_dwordx2 v[244:245], v[220:221], off offset:64
	global_load_dwordx2 v[246:247], v[220:221], off offset:80
	global_load_dwordx2 v[248:249], v[220:221], off offset:96
	global_load_dwordx2 v[250:251], v[220:221], off offset:112
.Ldil_nohoist:
	ds_read_b128 v[136:139], v215
	ds_read_b128 v[140:143], v215 offset:32
	ds_read_b128 v[132:135], v215 offset:64
	ds_read_b128 v[128:131], v215 offset:96
	s_mul_i32 s79, s74, s78
	s_add_i32 s79, s79, s75
	v_add_u32_e32 v216, s79, v190
	v_add_u32_e32 v1, 0xffffff80, v216
	v_mov_b32_e32 v14, v0
	v_mov_b32_e32 v15, v0
	v_cmp_lt_i32_e32 vcc, -1, v1
	v_mov_b32_e32 v1, v0
	v_mov_b32_e32 v2, v0
	v_mov_b32_e32 v3, v0
	v_mov_b32_e32 v4, v0
	v_mov_b32_e32 v5, v0
	v_mov_b32_e32 v6, v0
	v_mov_b32_e32 v7, v0
	v_mov_b32_e32 v8, v0
	v_mov_b32_e32 v9, v0
	v_mov_b32_e32 v10, v0
	v_mov_b32_e32 v11, v0
	v_mov_b32_e32 v12, v0
	v_mov_b32_e32 v13, v0
	v_mov_b64_e32 v[30:31], v[14:15]
	v_mov_b64_e32 v[46:47], v[14:15]
	v_add_u32_e32 v146, s79, v191
	v_mov_b32_e32 v147, 0
	v_mov_b64_e32 v[28:29], v[12:13]
	v_mov_b64_e32 v[26:27], v[10:11]
	v_mov_b64_e32 v[24:25], v[8:9]
	v_mov_b64_e32 v[22:23], v[6:7]
	v_mov_b64_e32 v[20:21], v[4:5]
	v_mov_b64_e32 v[18:19], v[2:3]
	v_mov_b64_e32 v[16:17], v[0:1]
	v_mov_b64_e32 v[44:45], v[12:13]
	v_mov_b64_e32 v[42:43], v[10:11]
	v_mov_b64_e32 v[40:41], v[8:9]
	v_mov_b64_e32 v[38:39], v[6:7]
	v_mov_b64_e32 v[36:37], v[4:5]
	v_mov_b64_e32 v[34:35], v[2:3]
	v_mov_b64_e32 v[32:33], v[0:1]
	s_and_saveexec_b64 s[34:35], vcc
	s_cbranch_execz .LBB0_752
	v_add_u32_e32 v1, v192, v194
	ds_read_b128 v[2:5], v1
	ds_read_b128 v[18:21], v1 offset:32
	s_movk_i32 s10, 0x81
	s_movk_i32 s18, 0x80
	s_waitcnt lgkmcnt(1)
	v_mfma_f32_32x32x16_bf16 v[2:17], v[2:5], v[136:139], 0
	s_waitcnt lgkmcnt(0)
	v_mfma_f32_32x32x16_bf16 v[2:17], v[18:21], v[140:143], v[2:17]
	ds_read_b128 v[18:21], v1 offset:64
	s_waitcnt lgkmcnt(0)
	v_mfma_f32_32x32x16_bf16 v[2:17], v[18:21], v[132:135], v[2:17]
	ds_read_b128 v[18:21], v1 offset:96
	v_add_u32_e32 v1, s79, v198
	v_add_u32_e32 v22, 0xffffff99, v1
	v_add_u32_e32 v23, 0xffffff92, v1
	v_add_u32_e32 v24, 0xffffff93, v1
	v_add_u32_e32 v25, 0xffffff90, v1
	v_add_u32_e32 v26, 0xffffff91, v1
	s_waitcnt lgkmcnt(0)
	v_mfma_f32_32x32x16_bf16 v[2:17], v[18:21], v[128:131], v[2:17]
	v_add_u32_e32 v19, 0xffffff9a, v1
	v_cmp_ge_i32_e32 vcc, v146, v19
	v_sub_u32_e32 v19, v146, v19
	v_cmp_gt_i32_e64 s[0:1], s10, v19
	s_and_b64 vcc, vcc, s[0:1]
	v_add_u32_e32 v20, 0xffffff9b, v1
	v_cndmask_b32_e32 v19, 0, v225, vcc
	v_cmp_ge_i32_e32 vcc, v146, v20
	v_sub_u32_e32 v20, v146, v20
	v_cmp_gt_i32_e64 s[0:1], s10, v20
	s_and_b64 vcc, vcc, s[0:1]
	v_add_u32_e32 v21, 0xffffff98, v1
	v_cndmask_b32_e32 v20, 0, v226, vcc
	v_cmp_ge_i32_e32 vcc, v146, v21
	v_sub_u32_e32 v21, v146, v21
	v_cmp_gt_i32_e64 s[0:1], s10, v21
	s_and_b64 vcc, vcc, s[0:1]
	v_cndmask_b32_e32 v21, 0, v228, vcc
	v_cmp_ge_i32_e32 vcc, v146, v22
	v_sub_u32_e32 v22, v146, v22
	v_cmp_gt_i32_e64 s[0:1], s10, v22
	s_and_b64 vcc, vcc, s[0:1]
	v_cndmask_b32_e32 v22, 0, v227, vcc
	v_cmp_ge_i32_e32 vcc, v146, v23
	v_sub_u32_e32 v23, v146, v23
	v_cmp_gt_i32_e64 s[0:1], s10, v23
	s_and_b64 vcc, vcc, s[0:1]
	v_cndmask_b32_e32 v23, 0, v230, vcc
	v_cmp_ge_i32_e32 vcc, v146, v24
	v_sub_u32_e32 v24, v146, v24
	v_cmp_gt_i32_e64 s[0:1], s10, v24
	s_and_b64 vcc, vcc, s[0:1]
	v_cndmask_b32_e32 v24, 0, v229, vcc
	v_cmp_ge_i32_e32 vcc, v146, v25
	v_sub_u32_e32 v25, v146, v25
	v_cmp_gt_i32_e64 s[0:1], s10, v25
	s_and_b64 s[2:3], vcc, s[0:1]
	v_cmp_ge_i32_e32 vcc, v146, v26
	v_sub_u32_e32 v26, v146, v26
	v_cmp_gt_i32_e64 s[0:1], s10, v26
	v_add_u32_e32 v27, 0xffffff8a, v1
	s_and_b64 s[4:5], vcc, s[0:1]
	v_cmp_lt_i32_e32 vcc, v146, v27
	v_sub_u32_e32 v27, v146, v27
	v_cmp_lt_i32_e64 s[0:1], s18, v27
	v_add_u32_e32 v28, 0xffffff8b, v1
	s_or_b64 s[6:7], vcc, s[0:1]
	v_cmp_lt_i32_e32 vcc, v146, v28
	v_sub_u32_e32 v28, v146, v28
	v_add_u32_e32 v18, 0xffffff80, v1
	v_cmp_lt_i32_e64 s[0:1], s18, v28
	s_or_b64 s[8:9], vcc, s[0:1]
	v_sub_u32_e32 v29, v18, v146
	s_movk_i32 s0, 0xff7f
	v_cmp_ge_i32_e32 vcc, v18, v146
	v_cmp_gt_i32_e64 s[0:1], s0, v29
	s_or_b64 s[0:1], vcc, s[0:1]
	v_cmp_le_i32_e32 vcc, v18, v146
	v_sub_u32_e32 v18, v146, v18
	v_cmp_gt_i32_e64 s[10:11], s10, v18
	v_add_u32_e32 v18, 0xffffff82, v1
	s_and_b64 vcc, vcc, s[10:11]
	v_cmp_lt_i32_e64 s[10:11], v146, v18
	v_sub_u32_e32 v18, v146, v18
	v_cmp_lt_i32_e64 s[12:13], s18, v18
	v_add_u32_e32 v30, 0xffffff83, v1
	s_or_b64 s[10:11], s[10:11], s[12:13]
	v_cmp_lt_i32_e64 s[12:13], v146, v30
	v_sub_u32_e32 v30, v146, v30
	v_cmp_lt_i32_e64 s[14:15], s18, v30
	v_add_u32_e32 v31, 0xffffff88, v1
	s_or_b64 s[12:13], s[12:13], s[14:15]
	v_cmp_lt_i32_e64 s[14:15], v146, v31
	v_sub_u32_e32 v31, v146, v31
	v_cmp_lt_i32_e64 s[16:17], s18, v31
	v_add_u32_e32 v1, 0xffffff89, v1
	s_or_b64 s[14:15], s[14:15], s[16:17]
	v_cmp_lt_i32_e64 s[16:17], v146, v1
	v_sub_u32_e32 v1, v146, v1
	v_cndmask_b32_e64 v27, 64, 0, s[6:7]
	v_cndmask_b32_e64 v28, v231, 0, s[8:9]
	v_cndmask_b32_e64 v29, 2, 0, s[0:1]
	v_cmp_lt_i32_e64 s[18:19], s18, v1
	v_cndmask_b32_e64 v18, 4, 0, s[10:11]
	v_cndmask_b32_e64 v30, 8, 0, s[12:13]
	s_or_b64 s[16:17], s[16:17], s[18:19]
	v_or3_b32 v27, v29, v28, v27
	v_cndmask_b32_e64 v31, 16, 0, s[14:15]
	v_cndmask_b32_e64 v1, 32, 0, s[16:17]
	v_or3_b32 v18, v18, v30, v27
	v_cndmask_b32_e64 v25, 0, v232, s[2:3]
	v_cndmask_b32_e64 v26, 0, v233, s[4:5]
	v_or3_b32 v1, v31, v1, v18
	v_or3_b32 v1, v1, v26, v25
	v_or3_b32 v1, v23, v24, v1
	v_or3_b32 v18, v21, v22, v1
	v_or3_b32 v19, v19, v20, v18
	v_and_b32_e32 v20, 0x8000, v19
	v_fma_f32 v17, v17, s33, -v148
	v_cmp_ne_u32_e64 s[18:19], 0, v20
	v_fma_f32 v16, v16, s33, -v148
	v_fma_f32 v2, v2, s33, -v148
	v_cndmask_b32_e64 v17, v234, v17, s[18:19]
	v_exp_f32_e32 v48, v17
	v_and_b32_e32 v17, 0x4000, v19
	v_cmp_ne_u32_e64 s[18:19], 0, v17
	v_fma_f32 v3, v3, s33, -v148
	v_cndmask_b32_e32 v2, v234, v2, vcc
	v_cndmask_b32_e64 v16, v234, v16, s[18:19]
	v_exp_f32_e32 v49, v16
	v_and_b32_e32 v16, 0x2000, v18
	v_fma_f32 v15, v15, s33, -v148
	v_cmp_ne_u32_e64 s[18:19], 0, v16
	v_and_b32_e32 v16, 0x1000, v18
	v_fma_f32 v4, v4, s33, -v148
	v_cndmask_b32_e64 v3, v3, v234, s[0:1]
	v_exp_f32_e32 v2, v2
	v_cndmask_b32_e64 v15, v234, v15, s[18:19]
	v_fma_f32 v14, v14, s33, -v148
	v_cmp_ne_u32_e64 s[18:19], 0, v16
	v_and_b32_e32 v16, 0x800, v1
	v_fma_f32 v5, v5, s33, -v148
	v_cndmask_b32_e64 v4, v4, v234, s[10:11]
	v_exp_f32_e32 v3, v3
	v_cndmask_b32_e64 v14, v234, v14, s[18:19]
	v_fma_f32 v13, v13, s33, -v148
	v_cmp_ne_u32_e64 s[18:19], 0, v16
	v_and_b32_e32 v1, 0x400, v1
	v_fma_f32 v6, v6, s33, -v148
	v_cndmask_b32_e64 v5, v5, v234, s[12:13]
	v_exp_f32_e32 v4, v4
	v_cndmask_b32_e64 v13, v234, v13, s[18:19]
	v_fma_f32 v12, v12, s33, -v148
	v_cmp_ne_u32_e64 s[18:19], 0, v1
	v_fma_f32 v7, v7, s33, -v148
	v_cndmask_b32_e64 v6, v6, v234, s[14:15]
	v_exp_f32_e32 v5, v5
	v_cndmask_b32_e64 v1, v234, v12, s[18:19]
	v_fma_f32 v8, v8, s33, -v148
	v_cndmask_b32_e64 v7, v7, v234, s[16:17]
	v_exp_f32_e32 v6, v6
	v_add_f32_e32 v12, 0, v2
	v_fma_f32 v9, v9, s33, -v148
	v_cndmask_b32_e64 v8, v8, v234, s[6:7]
	v_exp_f32_e32 v7, v7
	v_add_f32_e32 v12, v3, v12
	v_fma_f32 v10, v10, s33, -v148
	v_cndmask_b32_e64 v9, v9, v234, s[8:9]
	v_exp_f32_e32 v8, v8
	v_add_f32_e32 v12, v4, v12
	v_fma_f32 v11, v11, s33, -v148
	v_cndmask_b32_e64 v10, v234, v10, s[2:3]
	v_exp_f32_e32 v9, v9
	v_add_f32_e32 v12, v5, v12
	v_cndmask_b32_e64 v11, v234, v11, s[4:5]
	v_exp_f32_e32 v10, v10
	v_add_f32_e32 v12, v6, v12
	v_exp_f32_e32 v11, v11
	v_add_f32_e32 v12, v7, v12
	v_exp_f32_e32 v1, v1
	v_add_f32_e32 v12, v8, v12
	v_exp_f32_e32 v13, v13
	v_add_f32_e32 v12, v9, v12
	v_exp_f32_e32 v14, v14
	v_add_f32_e32 v12, v10, v12
	v_exp_f32_e32 v15, v15
	v_add_f32_e32 v12, v11, v12
	v_add_f32_e32 v12, v1, v12
	v_add_f32_e32 v12, v13, v12
	v_add_f32_e32 v12, v14, v12
	v_add_f32_e32 v12, v15, v12
	v_add_f32_e32 v12, v49, v12
	v_add_f32_e32 v12, v48, v12
	v_add_f32_e32 v147, 0, v12
	v_add_u32_e32 v12, v193, v194
	v_cvt_pk_bf16_f32 v2, v2, v3
	v_cvt_pk_bf16_f32 v3, v4, v5
	v_cvt_pk_bf16_f32 v4, v6, v7
	v_cvt_pk_bf16_f32 v5, v8, v9
	ds_read_b64_tr_b16 v[6:7], v12 offset:55296
	ds_read_b64_tr_b16 v[8:9], v12 offset:56448
	s_waitcnt lgkmcnt(0)
	v_mfma_f32_32x32x16_bf16 v[32:47], v[6:9], v[2:5], 0
	ds_read_b64_tr_b16 v[6:7], v12 offset:55360
	ds_read_b64_tr_b16 v[8:9], v12 offset:56512
	s_waitcnt lgkmcnt(0)
	v_mfma_f32_32x32x16_bf16 v[16:31], v[6:9], v[2:5], 0
	ds_read_b64_tr_b16 v[6:7], v12 offset:57600
	ds_read_b64_tr_b16 v[8:9], v12 offset:58752
	v_cvt_pk_bf16_f32 v2, v10, v11
	v_cvt_pk_bf16_f32 v3, v1, v13
	v_cvt_pk_bf16_f32 v4, v14, v15
	v_cvt_pk_bf16_f32 v5, v49, v48
	s_waitcnt lgkmcnt(0)
	s_nop 0
	v_mfma_f32_32x32x16_bf16 v[32:47], v[6:9], v[2:5], v[32:47]
	ds_read_b64_tr_b16 v[6:7], v12 offset:57664
	ds_read_b64_tr_b16 v[8:9], v12 offset:58816
	s_waitcnt lgkmcnt(0)
	v_mfma_f32_32x32x16_bf16 v[16:31], v[6:9], v[2:5], v[16:31]

.LBB0_760:
	s_or_b64 exec, exec, s[34:35]
	s_ashr_i32 s0, s78, 31
	s_lshr_b32 s0, s0, 28
	s_add_i32 s1, s78, s0
	s_ashr_i32 s2, s1, 4
	s_abs_i32 s3, s2
	s_mul_hi_u32 s4, s3, s73
	s_mul_i32 s5, s4, s40
	ds_bpermute_b32 v1, v145, v147
	s_sub_i32 s3, s3, s5
	s_ashr_i32 s0, s1, 31
	s_add_i32 s5, s4, 1
	s_sub_i32 s6, s3, s40
	s_cmp_ge_u32 s3, s40
	s_cselect_b32 s4, s5, s4
	s_cselect_b32 s3, s6, s3
	s_add_i32 s5, s4, 1
	s_waitcnt lgkmcnt(0)
	v_add_f32_e32 v5, v147, v1
	s_cmp_ge_u32 s3, s40
	v_cmp_gt_f32_e32 vcc, s95, v5
	s_cselect_b32 s3, s5, s4
	s_xor_b32 s3, s3, s0
	v_cndmask_b32_e64 v1, 0, 32, vcc
	v_ldexp_f32 v1, v5, v1
	s_sub_i32 s0, s3, s0
	v_log_f32_e32 v1, v1
	s_mul_i32 s3, s0, s40
	s_and_b32 s1, s1, -16
	s_sub_i32 s3, s2, s3
	s_sub_i32 s2, s78, s1
	v_mov_b32_e32 v2, 0x42000000
	s_ashr_i32 s1, s0, 31
	v_cndmask_b32_e32 v2, 0, v2, vcc
	s_lshl_b64 s[0:1], s[0:1], 13
	s_ashr_i32 s4, s3, 31
	v_sub_f32_e32 v1, v1, v2
	v_ashrrev_i32_e32 v147, 31, v146
	s_add_u32 s0, s0, s3
	v_add_f32_e32 v1, v148, v1
	v_lshlrev_b64 v[2:3], s71, v[146:147]
	s_addc_u32 s1, s1, s4
	v_cndmask_b32_e64 v6, 0, 1, s[24:25]
	v_mov_b32_e32 v4, 0
	v_mul_f32_e32 v1, 0x3f317218, v1
	v_lshl_add_u64 v[2:3], s[0:1], 0, v[2:3]
	v_cmp_ne_u32_e64 s[0:1], 1, v6
	s_andn2_b64 vcc, exec, s[24:25]
	v_mov_b32_e32 v6, 1.0
	s_cbranch_vccnz .LBB0_762
	s_waitcnt vmcnt(0)
	v_mov_b32_e32 v4, v217
	v_max_f32_e32 v6, v1, v1
	s_mov_b32 s3, 0x3f317217
	s_waitcnt vmcnt(0)
	v_max_f32_e32 v7, v4, v4
	v_max_f32_e32 v6, v7, v6
	v_sub_f32_e32 v7, v4, v6
	v_sub_f32_e32 v8, v1, v6
	v_mul_f32_e32 v7, 0x3fb8aa3b, v7
	v_mul_f32_e32 v8, 0x3fb8aa3b, v8
	v_exp_f32_e32 v7, v7
	v_exp_f32_e32 v8, v8
	s_nop 0
	v_add_f32_e32 v7, v7, v8
	v_cmp_gt_f32_e32 vcc, s95, v7
	s_nop 1
	v_cndmask_b32_e64 v8, 0, 32, vcc
	v_ldexp_f32 v7, v7, v8
	v_log_f32_e32 v7, v7
	v_mov_b32_e32 v8, 0x41b17218
	v_cndmask_b32_e32 v8, 0, v8, vcc
	v_mul_f32_e32 v9, 0x3f317217, v7
	v_fma_f32 v9, v7, s3, -v9
	v_fmac_f32_e32 v9, 0x3377d1cf, v7
	s_mov_b32 s3, 0x7f800000
	v_fmac_f32_e32 v9, 0x3f317217, v7
	v_cmp_lt_f32_e64 vcc, |v7|, s3
	s_nop 1
	v_cndmask_b32_e32 v7, v7, v9, vcc
	v_sub_f32_e32 v7, v7, v8
	v_add_f32_e32 v7, v6, v7
	v_sub_f32_e32 v4, v4, v7
	v_sub_f32_e32 v1, v1, v7
	v_mul_f32_e32 v4, 0x3fb8aa3b, v4
	v_mul_f32_e32 v1, 0x3fb8aa3b, v1
	v_exp_f32_e32 v4, v4
	v_exp_f32_e32 v6, v1
	v_mov_b32_e32 v1, v7
